# strategy 2: prologue x->bf16 row loop, the four 16-byte loads of a row issued together with counted waits instead of load/store/vmcnt(0) per piece
# speedup vs baseline: 1.0088x; 1.0088x over previous
; DI unsigned pk2(float lo, float hi) { f32x2 v = {lo, hi}; bf16x2_t b = __builtin_convertvector(v, bf16x2_t); return __builtin_bit_cast(unsigned, b); }
; DI void phase_prologue(const Params& p, unsigned char* lds) {
;     ...
;   for (long row = (long)blockIdx.x * 8 + (tid >> 6); row < NTOK; row += (long)gridDim.x * 8) {
;     const float* xr = p.x_in + row * D_MODEL; bf16_t* xo = p.xb() + row * LDX;
;     float ss = 0.f;
; #pragma unroll
;     for (int u = 0; u < 4; ++u) {
;       const f32x4 v = *(const f32x4*)(xr + u * 256 + lane * 4);
;       ss += v[0] * v[0] + v[1] * v[1] + v[2] * v[2] + v[3] * v[3];
;       *(u32x2*)(xo + u * 256 + lane * 4) = (u32x2){pk2(v[0], v[1]), pk2(v[2], v[3])};
;     }
; #pragma unroll
;     for (int o = 32; o >= 1; o >>= 1) ss += __shfl_xor(ss, o);
;     if (lane < 8) p.part()[row * 16 + lane] = lane == 0 ? ss : 0.f;
;   }
.LBB0_161:
	global_load_dwordx4 v[20:23], v[10:11], off offset:-2048
	global_load_dwordx4 v[24:27], v[10:11], off offset:-1024
	global_load_dwordx4 v[28:31], v[10:11], off
	global_load_dwordx4 v[32:35], v[10:11], off offset:1024
	s_waitcnt vmcnt(3) lgkmcnt(0)
	v_cvt_pk_bf16_f32 v6, v20, v21
	v_cvt_pk_bf16_f32 v7, v22, v23
	global_store_dwordx2 v[4:5], v[6:7], off offset:-1024
	v_mul_f32_e32 v1, v21, v21
	v_fmac_f32_e32 v1, v20, v20
	v_fmac_f32_e32 v1, v22, v22
	v_fmac_f32_e32 v1, v23, v23
	s_waitcnt vmcnt(3)
	v_cvt_pk_bf16_f32 v6, v24, v25
	v_cvt_pk_bf16_f32 v7, v26, v27
	global_store_dwordx2 v[4:5], v[6:7], off offset:-512
	s_waitcnt vmcnt(3)
	v_cvt_pk_bf16_f32 v6, v28, v29
	v_cvt_pk_bf16_f32 v7, v30, v31
	global_store_dwordx2 v[4:5], v[6:7], off
	v_mul_f32_e32 v6, v25, v25
	v_fmac_f32_e32 v6, v24, v24
	v_fmac_f32_e32 v6, v26, v26
	v_fmac_f32_e32 v6, v27, v27
	v_add_f32_e32 v1, v1, v6
	v_mul_f32_e32 v6, v29, v29
	v_fmac_f32_e32 v6, v28, v28
	v_fmac_f32_e32 v6, v30, v30
	v_fmac_f32_e32 v6, v31, v31
	v_add_f32_e32 v1, v1, v6
	s_waitcnt vmcnt(3)
	v_mul_f32_e32 v6, v33, v33
	v_fmac_f32_e32 v6, v32, v32
	v_fmac_f32_e32 v6, v34, v34
	v_fmac_f32_e32 v6, v35, v35
	v_add_f32_e32 v1, v1, v6
	ds_bpermute_b32 v6, v13, v1
	v_cvt_pk_bf16_f32 v20, v32, v33
	v_cvt_pk_bf16_f32 v21, v34, v35
	global_store_dwordx2 v[4:5], v[20:21], off offset:512
	s_waitcnt lgkmcnt(0)
	v_add_f32_e32 v1, v1, v6
	ds_bpermute_b32 v6, v14, v1
	s_waitcnt lgkmcnt(0)
	v_add_f32_e32 v1, v1, v6
	ds_bpermute_b32 v6, v15, v1
	s_waitcnt lgkmcnt(0)
	v_add_f32_e32 v1, v1, v6
	ds_bpermute_b32 v6, v16, v1
	s_waitcnt lgkmcnt(0)
	v_add_f32_e32 v1, v1, v6
	ds_bpermute_b32 v6, v17, v1
	s_waitcnt lgkmcnt(0)
	v_add_f32_e32 v1, v1, v6
	ds_bpermute_b32 v6, v18, v1
	s_and_saveexec_b64 s[0:1], vcc
	s_cbranch_execz .LBB0_160
	s_waitcnt lgkmcnt(0)
	v_add_f32_e32 v1, v1, v6
	v_cndmask_b32_e64 v1, 0, v1, s[10:11]
	global_store_dword v[8:9], v1, off
	s_branch .LBB0_160
